# EpiIn: straight-line fast path for all non-rotary tiles (ssq loads hoisted, no per-unit vmcnt(0) drains, in-place bf16 pack, exec-masked stores for the partial column tile)
# speedup vs baseline: 1.0069x; 1.0052x over previous
.LBB0_496:
	s_add_i32 s46, s46, s86
	v_or_b32_e32 v178, s46, v155
	v_ashrrev_i32_e32 v179, 31, v178
	s_add_i32 s6, s76, -12
	s_cmp_lt_u32 s6, 5
	s_cbranch_scc0 .Lin_fast
	s_cmpk_lt_i32 s77, 0x80
	s_cbranch_scc1 .Lin_rope
	s_branch .Lin_fast

.Lin_fast:
	v_mad_i64_i32 v[246:247], s[42:43], v178, s79, 0
	v_lshl_add_u64 v[246:247], s[16:17], 0, v[246:247]
	v_lshl_add_u64 v[246:247], v[176:177], 1, v[246:247]
	v_lshl_add_u64 v[180:181], v[178:179], 2, s[62:63]
	s_movk_i32 s6, 0x1220
	v_or_b32_e32 v0, 32, v176
	v_cmp_gt_i32_e64 s[46:47], s6, v176
	v_cmp_gt_i32_e64 s[48:49], s6, v0
	v_mov_b32_e32 v183, 0
	s_and_b64 vcc, exec, s[44:45]
	s_cbranch_vccnz .Lin_fast_nossq
	global_load_dword v190, v[180:181], off
	global_load_dword v191, v[180:181], off offset:64
	global_load_dword v192, v[180:181], off offset:128
	global_load_dword v193, v[180:181], off offset:192
	global_load_dword v194, v[180:181], off offset:512
	global_load_dword v195, v[180:181], off offset:576
	global_load_dword v196, v[180:181], off offset:640
	global_load_dword v197, v[180:181], off offset:704
	s_waitcnt vmcnt(7)
	v_fmamk_f32 v182, v190, 0x3a000000, v207
	v_rsq_f32_e32 v182, v182
	s_nop 0
	v_pk_fma_f32 v[126:127], v[126:127], v[182:183], v[138:139] op_sel_hi:[1,0,1]
	v_pk_fma_f32 v[128:129], v[128:129], v[182:183], v[140:141] op_sel_hi:[1,0,1]
	v_pk_fma_f32 v[122:123], v[122:123], v[182:183], v[142:143] op_sel_hi:[1,0,1]
	v_pk_fma_f32 v[124:125], v[124:125], v[182:183], v[144:145] op_sel_hi:[1,0,1]
	v_cvt_pk_bf16_f32 v126, v126, v127
	v_cvt_pk_bf16_f32 v127, v128, v129
	v_cvt_pk_bf16_f32 v128, v122, v123
	v_cvt_pk_bf16_f32 v129, v124, v125
	v_lshl_add_u64 v[184:185], v[246:247], 0, 0
	s_and_saveexec_b64 s[42:43], s[46:47]
	global_store_dwordx4 v[184:185], v[126:129], off
	s_mov_b64 exec, s[42:43]
	v_pk_fma_f32 v[118:119], v[118:119], v[182:183], v[134:135] op_sel_hi:[1,0,1]
	v_pk_fma_f32 v[120:121], v[120:121], v[182:183], v[136:137] op_sel_hi:[1,0,1]
	v_pk_fma_f32 v[114:115], v[114:115], v[182:183], v[130:131] op_sel_hi:[1,0,1]
	v_pk_fma_f32 v[116:117], v[116:117], v[182:183], v[132:133] op_sel_hi:[1,0,1]
	v_cvt_pk_bf16_f32 v118, v118, v119
	v_cvt_pk_bf16_f32 v119, v120, v121
	v_cvt_pk_bf16_f32 v120, v114, v115
	v_cvt_pk_bf16_f32 v121, v116, v117
	s_and_saveexec_b64 s[42:43], s[48:49]
	global_store_dwordx4 v[184:185], v[118:121], off offset:64
	s_mov_b64 exec, s[42:43]
	s_waitcnt vmcnt(8)
	v_fmamk_f32 v182, v191, 0x3a000000, v207
	v_rsq_f32_e32 v182, v182
	s_nop 0
	v_pk_fma_f32 v[110:111], v[110:111], v[182:183], v[138:139] op_sel_hi:[1,0,1]
	v_pk_fma_f32 v[112:113], v[112:113], v[182:183], v[140:141] op_sel_hi:[1,0,1]
	v_pk_fma_f32 v[106:107], v[106:107], v[182:183], v[142:143] op_sel_hi:[1,0,1]
	v_pk_fma_f32 v[108:109], v[108:109], v[182:183], v[144:145] op_sel_hi:[1,0,1]
	v_cvt_pk_bf16_f32 v110, v110, v111
	v_cvt_pk_bf16_f32 v111, v112, v113
	v_cvt_pk_bf16_f32 v112, v106, v107
	v_cvt_pk_bf16_f32 v113, v108, v109
	s_mov_b64 s[42:43], 0x24400
	v_lshl_add_u64 v[184:185], v[246:247], 0, s[42:43]
	s_and_saveexec_b64 s[42:43], s[46:47]
	global_store_dwordx4 v[184:185], v[110:113], off
	s_mov_b64 exec, s[42:43]
	v_pk_fma_f32 v[102:103], v[102:103], v[182:183], v[134:135] op_sel_hi:[1,0,1]
	v_pk_fma_f32 v[104:105], v[104:105], v[182:183], v[136:137] op_sel_hi:[1,0,1]
	v_pk_fma_f32 v[98:99], v[98:99], v[182:183], v[130:131] op_sel_hi:[1,0,1]
	v_pk_fma_f32 v[100:101], v[100:101], v[182:183], v[132:133] op_sel_hi:[1,0,1]
	v_cvt_pk_bf16_f32 v102, v102, v103
	v_cvt_pk_bf16_f32 v103, v104, v105
	v_cvt_pk_bf16_f32 v104, v98, v99
	v_cvt_pk_bf16_f32 v105, v100, v101
	s_and_saveexec_b64 s[42:43], s[48:49]
	global_store_dwordx4 v[184:185], v[102:105], off offset:64
	s_mov_b64 exec, s[42:43]
	s_waitcnt vmcnt(9)
	v_fmamk_f32 v182, v192, 0x3a000000, v207
	v_rsq_f32_e32 v182, v182
	s_nop 0
	v_pk_fma_f32 v[94:95], v[94:95], v[182:183], v[138:139] op_sel_hi:[1,0,1]
	v_pk_fma_f32 v[96:97], v[96:97], v[182:183], v[140:141] op_sel_hi:[1,0,1]
	v_pk_fma_f32 v[90:91], v[90:91], v[182:183], v[142:143] op_sel_hi:[1,0,1]
	v_pk_fma_f32 v[92:93], v[92:93], v[182:183], v[144:145] op_sel_hi:[1,0,1]
	v_cvt_pk_bf16_f32 v94, v94, v95
	v_cvt_pk_bf16_f32 v95, v96, v97
	v_cvt_pk_bf16_f32 v96, v90, v91
	v_cvt_pk_bf16_f32 v97, v92, v93
	s_mov_b64 s[42:43], 0x48800
	v_lshl_add_u64 v[184:185], v[246:247], 0, s[42:43]
	s_and_saveexec_b64 s[42:43], s[46:47]
	global_store_dwordx4 v[184:185], v[94:97], off
	s_mov_b64 exec, s[42:43]
	v_pk_fma_f32 v[86:87], v[86:87], v[182:183], v[134:135] op_sel_hi:[1,0,1]
	v_pk_fma_f32 v[88:89], v[88:89], v[182:183], v[136:137] op_sel_hi:[1,0,1]
	v_pk_fma_f32 v[82:83], v[82:83], v[182:183], v[130:131] op_sel_hi:[1,0,1]
	v_pk_fma_f32 v[84:85], v[84:85], v[182:183], v[132:133] op_sel_hi:[1,0,1]
	v_cvt_pk_bf16_f32 v86, v86, v87
	v_cvt_pk_bf16_f32 v87, v88, v89
	v_cvt_pk_bf16_f32 v88, v82, v83
	v_cvt_pk_bf16_f32 v89, v84, v85
	s_and_saveexec_b64 s[42:43], s[48:49]
	global_store_dwordx4 v[184:185], v[86:89], off offset:64
	s_mov_b64 exec, s[42:43]
	s_waitcnt vmcnt(10)
	v_fmamk_f32 v182, v193, 0x3a000000, v207
	v_rsq_f32_e32 v182, v182
	s_nop 0
	v_pk_fma_f32 v[78:79], v[78:79], v[182:183], v[138:139] op_sel_hi:[1,0,1]
	v_pk_fma_f32 v[80:81], v[80:81], v[182:183], v[140:141] op_sel_hi:[1,0,1]
	v_pk_fma_f32 v[74:75], v[74:75], v[182:183], v[142:143] op_sel_hi:[1,0,1]
	v_pk_fma_f32 v[76:77], v[76:77], v[182:183], v[144:145] op_sel_hi:[1,0,1]
	v_cvt_pk_bf16_f32 v78, v78, v79
	v_cvt_pk_bf16_f32 v79, v80, v81
	v_cvt_pk_bf16_f32 v80, v74, v75
	v_cvt_pk_bf16_f32 v81, v76, v77
	s_mov_b64 s[42:43], 0x6cc00
	v_lshl_add_u64 v[184:185], v[246:247], 0, s[42:43]
	s_and_saveexec_b64 s[42:43], s[46:47]
	global_store_dwordx4 v[184:185], v[78:81], off
	s_mov_b64 exec, s[42:43]
	v_pk_fma_f32 v[70:71], v[70:71], v[182:183], v[134:135] op_sel_hi:[1,0,1]
	v_pk_fma_f32 v[72:73], v[72:73], v[182:183], v[136:137] op_sel_hi:[1,0,1]
	v_pk_fma_f32 v[66:67], v[66:67], v[182:183], v[130:131] op_sel_hi:[1,0,1]
	v_pk_fma_f32 v[68:69], v[68:69], v[182:183], v[132:133] op_sel_hi:[1,0,1]
	v_cvt_pk_bf16_f32 v70, v70, v71
	v_cvt_pk_bf16_f32 v71, v72, v73
	v_cvt_pk_bf16_f32 v72, v66, v67
	v_cvt_pk_bf16_f32 v73, v68, v69
	s_and_saveexec_b64 s[42:43], s[48:49]
	global_store_dwordx4 v[184:185], v[70:73], off offset:64
	s_mov_b64 exec, s[42:43]
	s_waitcnt vmcnt(11)
	v_fmamk_f32 v182, v194, 0x3a000000, v207
	v_rsq_f32_e32 v182, v182
	s_nop 0
	v_pk_fma_f32 v[62:63], v[62:63], v[182:183], v[138:139] op_sel_hi:[1,0,1]
	v_pk_fma_f32 v[64:65], v[64:65], v[182:183], v[140:141] op_sel_hi:[1,0,1]
	v_pk_fma_f32 v[58:59], v[58:59], v[182:183], v[142:143] op_sel_hi:[1,0,1]
	v_pk_fma_f32 v[60:61], v[60:61], v[182:183], v[144:145] op_sel_hi:[1,0,1]
	v_cvt_pk_bf16_f32 v62, v62, v63
	v_cvt_pk_bf16_f32 v63, v64, v65
	v_cvt_pk_bf16_f32 v64, v58, v59
	v_cvt_pk_bf16_f32 v65, v60, v61
	s_mov_b64 s[42:43], 0x122000
	v_lshl_add_u64 v[184:185], v[246:247], 0, s[42:43]
	s_and_saveexec_b64 s[42:43], s[46:47]
	global_store_dwordx4 v[184:185], v[62:65], off
	s_mov_b64 exec, s[42:43]
	v_pk_fma_f32 v[54:55], v[54:55], v[182:183], v[134:135] op_sel_hi:[1,0,1]
	v_pk_fma_f32 v[56:57], v[56:57], v[182:183], v[136:137] op_sel_hi:[1,0,1]
	v_pk_fma_f32 v[50:51], v[50:51], v[182:183], v[130:131] op_sel_hi:[1,0,1]
	v_pk_fma_f32 v[52:53], v[52:53], v[182:183], v[132:133] op_sel_hi:[1,0,1]
	v_cvt_pk_bf16_f32 v54, v54, v55
	v_cvt_pk_bf16_f32 v55, v56, v57
	v_cvt_pk_bf16_f32 v56, v50, v51
	v_cvt_pk_bf16_f32 v57, v52, v53
	s_and_saveexec_b64 s[42:43], s[48:49]
	global_store_dwordx4 v[184:185], v[54:57], off offset:64
	s_mov_b64 exec, s[42:43]
	s_waitcnt vmcnt(12)
	v_fmamk_f32 v182, v195, 0x3a000000, v207
	v_rsq_f32_e32 v182, v182
	s_nop 0
	v_pk_fma_f32 v[46:47], v[46:47], v[182:183], v[138:139] op_sel_hi:[1,0,1]
	v_pk_fma_f32 v[48:49], v[48:49], v[182:183], v[140:141] op_sel_hi:[1,0,1]
	v_pk_fma_f32 v[42:43], v[42:43], v[182:183], v[142:143] op_sel_hi:[1,0,1]
	v_pk_fma_f32 v[44:45], v[44:45], v[182:183], v[144:145] op_sel_hi:[1,0,1]
	v_cvt_pk_bf16_f32 v46, v46, v47
	v_cvt_pk_bf16_f32 v47, v48, v49
	v_cvt_pk_bf16_f32 v48, v42, v43
	v_cvt_pk_bf16_f32 v49, v44, v45
	s_mov_b64 s[42:43], 0x146400
	v_lshl_add_u64 v[184:185], v[246:247], 0, s[42:43]
	s_and_saveexec_b64 s[42:43], s[46:47]
	global_store_dwordx4 v[184:185], v[46:49], off
	s_mov_b64 exec, s[42:43]
	v_pk_fma_f32 v[38:39], v[38:39], v[182:183], v[134:135] op_sel_hi:[1,0,1]
	v_pk_fma_f32 v[40:41], v[40:41], v[182:183], v[136:137] op_sel_hi:[1,0,1]
	v_pk_fma_f32 v[34:35], v[34:35], v[182:183], v[130:131] op_sel_hi:[1,0,1]
	v_pk_fma_f32 v[36:37], v[36:37], v[182:183], v[132:133] op_sel_hi:[1,0,1]
	v_cvt_pk_bf16_f32 v38, v38, v39
	v_cvt_pk_bf16_f32 v39, v40, v41
	v_cvt_pk_bf16_f32 v40, v34, v35
	v_cvt_pk_bf16_f32 v41, v36, v37
	s_and_saveexec_b64 s[42:43], s[48:49]
	global_store_dwordx4 v[184:185], v[38:41], off offset:64
	s_mov_b64 exec, s[42:43]
	s_waitcnt vmcnt(13)
	v_fmamk_f32 v182, v196, 0x3a000000, v207
	v_rsq_f32_e32 v182, v182
	s_nop 0
	v_pk_fma_f32 v[30:31], v[30:31], v[182:183], v[138:139] op_sel_hi:[1,0,1]
	v_pk_fma_f32 v[32:33], v[32:33], v[182:183], v[140:141] op_sel_hi:[1,0,1]
	v_pk_fma_f32 v[26:27], v[26:27], v[182:183], v[142:143] op_sel_hi:[1,0,1]
	v_pk_fma_f32 v[28:29], v[28:29], v[182:183], v[144:145] op_sel_hi:[1,0,1]
	v_cvt_pk_bf16_f32 v30, v30, v31
	v_cvt_pk_bf16_f32 v31, v32, v33
	v_cvt_pk_bf16_f32 v32, v26, v27
	v_cvt_pk_bf16_f32 v33, v28, v29
	s_mov_b64 s[42:43], 0x16a800
	v_lshl_add_u64 v[184:185], v[246:247], 0, s[42:43]
	s_and_saveexec_b64 s[42:43], s[46:47]
	global_store_dwordx4 v[184:185], v[30:33], off
	s_mov_b64 exec, s[42:43]
	v_pk_fma_f32 v[22:23], v[22:23], v[182:183], v[134:135] op_sel_hi:[1,0,1]
	v_pk_fma_f32 v[24:25], v[24:25], v[182:183], v[136:137] op_sel_hi:[1,0,1]
	v_pk_fma_f32 v[18:19], v[18:19], v[182:183], v[130:131] op_sel_hi:[1,0,1]
	v_pk_fma_f32 v[20:21], v[20:21], v[182:183], v[132:133] op_sel_hi:[1,0,1]
	v_cvt_pk_bf16_f32 v22, v22, v23
	v_cvt_pk_bf16_f32 v23, v24, v25
	v_cvt_pk_bf16_f32 v24, v18, v19
	v_cvt_pk_bf16_f32 v25, v20, v21
	s_and_saveexec_b64 s[42:43], s[48:49]
	global_store_dwordx4 v[184:185], v[22:25], off offset:64
	s_mov_b64 exec, s[42:43]
	s_waitcnt vmcnt(14)
	v_fmamk_f32 v182, v197, 0x3a000000, v207
	v_rsq_f32_e32 v182, v182
	s_nop 0
	v_pk_fma_f32 v[14:15], v[14:15], v[182:183], v[138:139] op_sel_hi:[1,0,1]
	v_pk_fma_f32 v[16:17], v[16:17], v[182:183], v[140:141] op_sel_hi:[1,0,1]
	v_pk_fma_f32 v[10:11], v[10:11], v[182:183], v[142:143] op_sel_hi:[1,0,1]
	v_pk_fma_f32 v[12:13], v[12:13], v[182:183], v[144:145] op_sel_hi:[1,0,1]
	v_cvt_pk_bf16_f32 v14, v14, v15
	v_cvt_pk_bf16_f32 v15, v16, v17
	v_cvt_pk_bf16_f32 v16, v10, v11
	v_cvt_pk_bf16_f32 v17, v12, v13
	s_mov_b64 s[42:43], 0x18ec00
	v_lshl_add_u64 v[184:185], v[246:247], 0, s[42:43]
	s_and_saveexec_b64 s[42:43], s[46:47]
	global_store_dwordx4 v[184:185], v[14:17], off
	s_mov_b64 exec, s[42:43]
	v_pk_fma_f32 v[6:7], v[6:7], v[182:183], v[134:135] op_sel_hi:[1,0,1]
	v_pk_fma_f32 v[8:9], v[8:9], v[182:183], v[136:137] op_sel_hi:[1,0,1]
	v_pk_fma_f32 v[2:3], v[2:3], v[182:183], v[130:131] op_sel_hi:[1,0,1]
	v_pk_fma_f32 v[4:5], v[4:5], v[182:183], v[132:133] op_sel_hi:[1,0,1]
	v_cvt_pk_bf16_f32 v6, v6, v7
	v_cvt_pk_bf16_f32 v7, v8, v9
	v_cvt_pk_bf16_f32 v8, v2, v3
	v_cvt_pk_bf16_f32 v9, v4, v5
	s_and_saveexec_b64 s[42:43], s[48:49]
	global_store_dwordx4 v[184:185], v[6:9], off offset:64
	s_mov_b64 exec, s[42:43]
	s_branch .LBB0_375
.Lin_fast_nossq:
	v_pk_add_f32 v[126:127], v[126:127], v[138:139]
	v_pk_add_f32 v[128:129], v[128:129], v[140:141]
	v_pk_add_f32 v[122:123], v[122:123], v[142:143]
	v_pk_add_f32 v[124:125], v[124:125], v[144:145]
	v_cvt_pk_bf16_f32 v126, v126, v127
	v_cvt_pk_bf16_f32 v127, v128, v129
	v_cvt_pk_bf16_f32 v128, v122, v123
	v_cvt_pk_bf16_f32 v129, v124, v125
	v_lshl_add_u64 v[184:185], v[246:247], 0, 0
	s_and_saveexec_b64 s[42:43], s[46:47]
	global_store_dwordx4 v[184:185], v[126:129], off
	s_mov_b64 exec, s[42:43]
	v_pk_add_f32 v[118:119], v[118:119], v[134:135]
	v_pk_add_f32 v[120:121], v[120:121], v[136:137]
	v_pk_add_f32 v[114:115], v[114:115], v[130:131]
	v_pk_add_f32 v[116:117], v[116:117], v[132:133]
	v_cvt_pk_bf16_f32 v118, v118, v119
	v_cvt_pk_bf16_f32 v119, v120, v121
	v_cvt_pk_bf16_f32 v120, v114, v115
	v_cvt_pk_bf16_f32 v121, v116, v117
	s_and_saveexec_b64 s[42:43], s[48:49]
	global_store_dwordx4 v[184:185], v[118:121], off offset:64
	s_mov_b64 exec, s[42:43]
	v_pk_add_f32 v[110:111], v[110:111], v[138:139]
	v_pk_add_f32 v[112:113], v[112:113], v[140:141]
	v_pk_add_f32 v[106:107], v[106:107], v[142:143]
	v_pk_add_f32 v[108:109], v[108:109], v[144:145]
	v_cvt_pk_bf16_f32 v110, v110, v111
	v_cvt_pk_bf16_f32 v111, v112, v113
	v_cvt_pk_bf16_f32 v112, v106, v107
	v_cvt_pk_bf16_f32 v113, v108, v109
	s_mov_b64 s[42:43], 0x24400
	v_lshl_add_u64 v[184:185], v[246:247], 0, s[42:43]
	s_and_saveexec_b64 s[42:43], s[46:47]
	global_store_dwordx4 v[184:185], v[110:113], off
	s_mov_b64 exec, s[42:43]
	v_pk_add_f32 v[102:103], v[102:103], v[134:135]
	v_pk_add_f32 v[104:105], v[104:105], v[136:137]
	v_pk_add_f32 v[98:99], v[98:99], v[130:131]
	v_pk_add_f32 v[100:101], v[100:101], v[132:133]
	v_cvt_pk_bf16_f32 v102, v102, v103
	v_cvt_pk_bf16_f32 v103, v104, v105
	v_cvt_pk_bf16_f32 v104, v98, v99
	v_cvt_pk_bf16_f32 v105, v100, v101
	s_and_saveexec_b64 s[42:43], s[48:49]
	global_store_dwordx4 v[184:185], v[102:105], off offset:64
	s_mov_b64 exec, s[42:43]
	v_pk_add_f32 v[94:95], v[94:95], v[138:139]
	v_pk_add_f32 v[96:97], v[96:97], v[140:141]
	v_pk_add_f32 v[90:91], v[90:91], v[142:143]
	v_pk_add_f32 v[92:93], v[92:93], v[144:145]
	v_cvt_pk_bf16_f32 v94, v94, v95
	v_cvt_pk_bf16_f32 v95, v96, v97
	v_cvt_pk_bf16_f32 v96, v90, v91
	v_cvt_pk_bf16_f32 v97, v92, v93
	s_mov_b64 s[42:43], 0x48800
	v_lshl_add_u64 v[184:185], v[246:247], 0, s[42:43]
	s_and_saveexec_b64 s[42:43], s[46:47]
	global_store_dwordx4 v[184:185], v[94:97], off
	s_mov_b64 exec, s[42:43]
	v_pk_add_f32 v[86:87], v[86:87], v[134:135]
	v_pk_add_f32 v[88:89], v[88:89], v[136:137]
	v_pk_add_f32 v[82:83], v[82:83], v[130:131]
	v_pk_add_f32 v[84:85], v[84:85], v[132:133]
	v_cvt_pk_bf16_f32 v86, v86, v87
	v_cvt_pk_bf16_f32 v87, v88, v89
	v_cvt_pk_bf16_f32 v88, v82, v83
	v_cvt_pk_bf16_f32 v89, v84, v85
	s_and_saveexec_b64 s[42:43], s[48:49]
	global_store_dwordx4 v[184:185], v[86:89], off offset:64
	s_mov_b64 exec, s[42:43]
	v_pk_add_f32 v[78:79], v[78:79], v[138:139]
	v_pk_add_f32 v[80:81], v[80:81], v[140:141]
	v_pk_add_f32 v[74:75], v[74:75], v[142:143]
	v_pk_add_f32 v[76:77], v[76:77], v[144:145]
	v_cvt_pk_bf16_f32 v78, v78, v79
	v_cvt_pk_bf16_f32 v79, v80, v81
	v_cvt_pk_bf16_f32 v80, v74, v75
	v_cvt_pk_bf16_f32 v81, v76, v77
	s_mov_b64 s[42:43], 0x6cc00
	v_lshl_add_u64 v[184:185], v[246:247], 0, s[42:43]
	s_and_saveexec_b64 s[42:43], s[46:47]
	global_store_dwordx4 v[184:185], v[78:81], off
	s_mov_b64 exec, s[42:43]
	v_pk_add_f32 v[70:71], v[70:71], v[134:135]
	v_pk_add_f32 v[72:73], v[72:73], v[136:137]
	v_pk_add_f32 v[66:67], v[66:67], v[130:131]
	v_pk_add_f32 v[68:69], v[68:69], v[132:133]
	v_cvt_pk_bf16_f32 v70, v70, v71
	v_cvt_pk_bf16_f32 v71, v72, v73
	v_cvt_pk_bf16_f32 v72, v66, v67
	v_cvt_pk_bf16_f32 v73, v68, v69
	s_and_saveexec_b64 s[42:43], s[48:49]
	global_store_dwordx4 v[184:185], v[70:73], off offset:64
	s_mov_b64 exec, s[42:43]
	v_pk_add_f32 v[62:63], v[62:63], v[138:139]
	v_pk_add_f32 v[64:65], v[64:65], v[140:141]
	v_pk_add_f32 v[58:59], v[58:59], v[142:143]
	v_pk_add_f32 v[60:61], v[60:61], v[144:145]
	v_cvt_pk_bf16_f32 v62, v62, v63
	v_cvt_pk_bf16_f32 v63, v64, v65
	v_cvt_pk_bf16_f32 v64, v58, v59
	v_cvt_pk_bf16_f32 v65, v60, v61
	s_mov_b64 s[42:43], 0x122000
	v_lshl_add_u64 v[184:185], v[246:247], 0, s[42:43]
	s_and_saveexec_b64 s[42:43], s[46:47]
	global_store_dwordx4 v[184:185], v[62:65], off
	s_mov_b64 exec, s[42:43]
	v_pk_add_f32 v[54:55], v[54:55], v[134:135]
	v_pk_add_f32 v[56:57], v[56:57], v[136:137]
	v_pk_add_f32 v[50:51], v[50:51], v[130:131]
	v_pk_add_f32 v[52:53], v[52:53], v[132:133]
	v_cvt_pk_bf16_f32 v54, v54, v55
	v_cvt_pk_bf16_f32 v55, v56, v57
	v_cvt_pk_bf16_f32 v56, v50, v51
	v_cvt_pk_bf16_f32 v57, v52, v53
	s_and_saveexec_b64 s[42:43], s[48:49]
	global_store_dwordx4 v[184:185], v[54:57], off offset:64
	s_mov_b64 exec, s[42:43]
	v_pk_add_f32 v[46:47], v[46:47], v[138:139]
	v_pk_add_f32 v[48:49], v[48:49], v[140:141]
	v_pk_add_f32 v[42:43], v[42:43], v[142:143]
	v_pk_add_f32 v[44:45], v[44:45], v[144:145]
	v_cvt_pk_bf16_f32 v46, v46, v47
	v_cvt_pk_bf16_f32 v47, v48, v49
	v_cvt_pk_bf16_f32 v48, v42, v43
	v_cvt_pk_bf16_f32 v49, v44, v45
	s_mov_b64 s[42:43], 0x146400
	v_lshl_add_u64 v[184:185], v[246:247], 0, s[42:43]
	s_and_saveexec_b64 s[42:43], s[46:47]
	global_store_dwordx4 v[184:185], v[46:49], off
	s_mov_b64 exec, s[42:43]
	v_pk_add_f32 v[38:39], v[38:39], v[134:135]
	v_pk_add_f32 v[40:41], v[40:41], v[136:137]
	v_pk_add_f32 v[34:35], v[34:35], v[130:131]
	v_pk_add_f32 v[36:37], v[36:37], v[132:133]
	v_cvt_pk_bf16_f32 v38, v38, v39
	v_cvt_pk_bf16_f32 v39, v40, v41
	v_cvt_pk_bf16_f32 v40, v34, v35
	v_cvt_pk_bf16_f32 v41, v36, v37
	s_and_saveexec_b64 s[42:43], s[48:49]
	global_store_dwordx4 v[184:185], v[38:41], off offset:64
	s_mov_b64 exec, s[42:43]
	v_pk_add_f32 v[30:31], v[30:31], v[138:139]
	v_pk_add_f32 v[32:33], v[32:33], v[140:141]
	v_pk_add_f32 v[26:27], v[26:27], v[142:143]
	v_pk_add_f32 v[28:29], v[28:29], v[144:145]
	v_cvt_pk_bf16_f32 v30, v30, v31
	v_cvt_pk_bf16_f32 v31, v32, v33
	v_cvt_pk_bf16_f32 v32, v26, v27
	v_cvt_pk_bf16_f32 v33, v28, v29
	s_mov_b64 s[42:43], 0x16a800
	v_lshl_add_u64 v[184:185], v[246:247], 0, s[42:43]
	s_and_saveexec_b64 s[42:43], s[46:47]
	global_store_dwordx4 v[184:185], v[30:33], off
	s_mov_b64 exec, s[42:43]
	v_pk_add_f32 v[22:23], v[22:23], v[134:135]
	v_pk_add_f32 v[24:25], v[24:25], v[136:137]
	v_pk_add_f32 v[18:19], v[18:19], v[130:131]
	v_pk_add_f32 v[20:21], v[20:21], v[132:133]
	v_cvt_pk_bf16_f32 v22, v22, v23
	v_cvt_pk_bf16_f32 v23, v24, v25
	v_cvt_pk_bf16_f32 v24, v18, v19
	v_cvt_pk_bf16_f32 v25, v20, v21
	s_and_saveexec_b64 s[42:43], s[48:49]
	global_store_dwordx4 v[184:185], v[22:25], off offset:64
	s_mov_b64 exec, s[42:43]
	v_pk_add_f32 v[14:15], v[14:15], v[138:139]
	v_pk_add_f32 v[16:17], v[16:17], v[140:141]
	v_pk_add_f32 v[10:11], v[10:11], v[142:143]
	v_pk_add_f32 v[12:13], v[12:13], v[144:145]
	v_cvt_pk_bf16_f32 v14, v14, v15
	v_cvt_pk_bf16_f32 v15, v16, v17
	v_cvt_pk_bf16_f32 v16, v10, v11
	v_cvt_pk_bf16_f32 v17, v12, v13
	s_mov_b64 s[42:43], 0x18ec00
	v_lshl_add_u64 v[184:185], v[246:247], 0, s[42:43]
	s_and_saveexec_b64 s[42:43], s[46:47]
	global_store_dwordx4 v[184:185], v[14:17], off
	s_mov_b64 exec, s[42:43]
	v_pk_add_f32 v[6:7], v[6:7], v[134:135]
	v_pk_add_f32 v[8:9], v[8:9], v[136:137]
	v_pk_add_f32 v[2:3], v[2:3], v[130:131]
	v_pk_add_f32 v[4:5], v[4:5], v[132:133]
	v_cvt_pk_bf16_f32 v6, v6, v7
	v_cvt_pk_bf16_f32 v7, v8, v9
	v_cvt_pk_bf16_f32 v8, v2, v3
	v_cvt_pk_bf16_f32 v9, v4, v5
	s_and_saveexec_b64 s[42:43], s[48:49]
	global_store_dwordx4 v[184:185], v[6:9], off offset:64
	s_mov_b64 exec, s[42:43]
	s_branch .LBB0_375
